# stagger: sibling groups with odd M-tile index start the proj..in chain ~14 us late (4 x s_sleep 127) so their memory-bound epilogues overlap the other groups' K loops
# speedup vs baseline: 1.0429x; 1.0060x over previous
.LBB0_539:
	s_or_b64 exec, exec, s[0:1]
	v_mov_b32_e32 v0, v154
	v_readlane_b32 s6, v253, 0
	s_waitcnt lgkmcnt(0)
	s_barrier
	v_readlane_b32 s8, v253, 0
	s_bitcmp1_b32 s8, 3
	s_cbranch_scc0 .Lstag_skip
	s_sleep 127
	s_sleep 127
	s_sleep 127
	s_sleep 127
.Lstag_skip:
	s_cmpk_gt_i32 s6, 0xff
	s_cbranch_scc1 .LBB0_546
	v_readlane_b32 s0, v254, 24
	v_readlane_b32 s1, v254, 60
	s_add_u32 s7, s0, s1
	v_readlane_b32 s0, v254, 25
	s_addc_u32 s8, s0, 0
	s_lshl_b32 s9, s6, 3
	s_branch .LBB0_542
